# static s_setprio 1 on the LEADING wave half (wr=0) instead of the trailing half; otherwise identical to v72 (prologue de-serialisation + attention store transposition)
# baseline (speedup 1.0000x reference)
; template <class Epi, class Sched, bool ALIGN_EPI = false, bool SP2 = false>
; __device__ __forceinline__ void gemm_phase(PG8_LAS unsigned char* lds, const Gemm g, const Sched& S, const Epi& E, const int tid_in) {
;     ...
;         const bool has_next = S.next(ui + 1, nxt);
;         const char* nA = has_next ? (const char*)g.A + (size_t)nxt.pm * tstep : cA; const char* nB = has_next ? (const char*)g.Bt + (size_t)nxt.pn * tstep : cB;
;         for (int t = 0; t < nt; t += 2) {
;             if (t == E.mid_t) E.mid(acc, cur, wr, wc, fr, fq);
;             const bool last = (t == nt - 2);
;             const char* a1 = cA + (size_t)(t + 1) * kstep;
;             const char* a2 = last ? nA : cA + (size_t)(t + 2) * kstep; const char* b2 = last ? nB : cB + (size_t)(t + 2) * kstep;
;             const char* a3 = a2 + kstep; const char* b3 = b2 + kstep;
;             if (last && has_next) S.a_ready(nxt);
.LBB0_138:
	v_lshl_add_u32 v232, s48, 8, v221
	s_add_u32 s48, s46, 0x100
	s_addc_u32 s49, s47, 0
	s_add_u32 s0, s44, 0x80
	s_addc_u32 s1, s45, 0
	v_mov_b32_e32 v2, 0
	v_lshl_or_b32 v233, s55, 8, v229
	v_lshl_add_u64 v[208:209], s[0:1], 0, v[204:205]
	v_lshl_add_u64 v[210:211], s[0:1], 0, v[206:207]
	s_and_b64 vcc, exec, s[20:21]
	s_cbranch_vccz .Lnoprio
	s_setprio 1
